# NSA tile loops: first two K-fragment LDS reads issued at the top of the tile, before the next tile's address arithmetic and LDS-DMA issue (which uses the freed staging registers)
# baseline (speedup 1.0000x reference)
; #define LAS __attribute__((address_space(3)))
; #define NSA_LOADT(kb_, vb_, pitch_) do { int ln_ = lane; asm volatile("" : "+v"(ln_));   \
;         kreg = *(const u32x4*)((kb_) + (unsigned)(ln_ * (pitch_) + wid * 8)); vreg = *(const u32x4*)((vb_) + (unsigned)((16 * (wid & 3) + (ln_ >> 2)) * (pitch_) + (wid >> 2) * 32 + (ln_ & 3) * 8)); } while (0)
; __device__ __forceinline__ void nsa_qk(f32x16& p0, f32x16& p1, const LAS unsigned char* kslot, const bf16x8v (&qr)[4], int r32, int hi) {
;     const LAS unsigned char* kb = kslot + hi * 1024 + r32 * 16;
;     f32x16 z;
; #pragma unroll
;     for (int r = 0; r < 16; ++r) z[r] = 0.f;
;     p0 = z; p1 = z;
; #pragma unroll
;     for (int d0 = 0; d0 < 4; ++d0) { const bf16x8v b0 = *(const LAS bf16x8v*)(kb + d0 * 2048), b1 = *(const LAS bf16x8v*)(kb + d0 * 2048 + 512);
;         p0 = __builtin_amdgcn_mfma_f32_32x32x16_bf16(b0, qr[d0], p0, 0, 0, 0); p1 = __builtin_amdgcn_mfma_f32_32x32x16_bf16(b1, qr[d0], p1, 0, 0, 0); }
; }
; __device__ __forceinline__ void nsa_unit(const Ctx& c, int l, int b, int n, int qt) {
;     ...
;             const bool more = rem != 0ull; int jn = 0;
;             if (more) { jn = __builtin_ctzll(rem); rem &= rem - 1; NSA_LOADT(Kb + (size_t)jn * 64 * HW, Vb + (size_t)jn * 64 * HW, HW); }
;             f32x16 p0, p1;
;             nsa_qk(p0, p1, lds + NL_KS + cur * 8192, qr, r32, hi);
.LBB0_1323:
	s_lshl_b32 s20, s42, 13
	v_add_u32_e32 v0, s20, v236
	ds_read_b128 v[2:5], v0 offset:1024
	ds_read_b128 v[6:9], v0 offset:1536
	s_cmp_eq_u64 s[2:3], 0
	s_cselect_b64 s[6:7], -1, 0
	s_cmp_lg_u64 s[2:3], 0
	s_mov_b64 s[4:5], 0
	s_cselect_b64 s[36:37], -1, 0
	s_and_b64 vcc, exec, s[6:7]
	s_mov_b32 s43, 0
	s_cbranch_vccnz .LBB0_1325
	s_flbit_i32_b64 s43, s[2:3]
	s_sub_i32 s43, 63, s43
	s_mov_b64 s[4:5], s[2:3]
	s_bitset0_b64 s[4:5], s43
	v_mov_b32_e32 v148, v247
	s_mul_i32 s2, s43, 0x70000
	s_add_u32 s2, s28, s2
	v_mul_lo_u32 v144, v148, s21
	s_addc_u32 s3, s29, 0
	s_add_u32 s2, s2, 0x600
	s_addc_u32 s3, s3, 0
	v_mov_b32_e32 v145, 0
	v_add_u32_e32 v144, s1, v144
	v_lshl_add_u64 v[146:147], v[144:145], 1, s[2:3]
	v_lshrrev_b32_e32 v144, 2, v148
	v_add_u32_e32 v144, s22, v144
	v_mul_lo_u32 v144, v144, s21
	s_add_u32 s2, s2, 0x100
	s_addc_u32 s3, s3, 0
	v_add_u32_e32 v144, s23, v144
	v_lshlrev_b32_e32 v148, 3, v148
	v_and_or_b32 v144, v148, 24, v144
	v_lshl_add_u64 v[148:149], v[144:145], 1, s[2:3]
	s_xor_b32 s9, s42, 1
	s_lshl_b32 s9, s9, 13
	s_add_i32 s9, s9, s26
	s_add_i32 m0, s9, 0x400
	s_nop 0
	global_load_lds_dwordx4 v[146:147], off
	s_add_i32 m0, s9, 0x4400
	s_nop 0
	global_load_lds_dwordx4 v[148:149], off
; __device__ __forceinline__ void nsa_scores(f32x16& p0, f32x16& p1, float Ap, float slk, int thrp, bool flip) {
; #pragma unroll
;     for (int r = 0; r < 16; ++r) { const int cr = (r & 3) + 8 * (r >> 2);
;         const bool v0 = (cr <= thrp) != flip, v1 = (cr + 32 <= thrp) != flip;
;         p0[r] = v0 ? fmaf(p0[r], C2S, fmaf(slk, (float)cr, Ap)) : SNEG; p1[r] = v1 ? fmaf(p1[r], C2S, fmaf(slk, (float)(cr + 32), Ap)) : SNEG; }
; }
; __device__ __forceinline__ void nsa_unit(const Ctx& c, int l, int b, int n, int qt) {
;     ...
;             nsa_qk(p0, p1, lds + NL_KS + cur * 8192, qr, r32, hi);
;             const bool sel = (mq >> j) & 1ull;
;             bool on = true;
;             if (j < qt) { nsa_scores_all(p0, p1, -sl2 * (float)(t - 64 * j) + sl2 * (float)(4 * hi), sl2); on = sel; }
;             else nsa_scores(p0, p1, -sl2 * (float)(t - 64 * j) + sl2 * (float)(4 * hi), sl2, (sel ? tq : -1) - 4 * hi, false);
.LBB0_1325:
	s_lshl_b32 s9, s8, 6
	s_cmp_ge_u32 s8, s46
	s_mov_b64 s[16:17], -1
	s_waitcnt lgkmcnt(1)
	v_mfma_f32_32x32x16_bf16 v[112:127], v[2:5], v[176:179], 0
	s_waitcnt lgkmcnt(0)
	v_mfma_f32_32x32x16_bf16 v[96:111], v[6:9], v[176:179], 0
	ds_read_b128 v[2:5], v0 offset:3072
	ds_read_b128 v[6:9], v0 offset:3584
	s_waitcnt lgkmcnt(1)
	v_mfma_f32_32x32x16_bf16 v[112:127], v[2:5], v[180:183], v[112:127]
	s_waitcnt lgkmcnt(0)
	v_mfma_f32_32x32x16_bf16 v[96:111], v[6:9], v[180:183], v[96:111]
	ds_read_b128 v[2:5], v0 offset:5120
	ds_read_b128 v[6:9], v0 offset:5632
	s_waitcnt lgkmcnt(1)
	v_mfma_f32_32x32x16_bf16 v[112:127], v[2:5], v[184:187], v[112:127]
	s_waitcnt lgkmcnt(0)
	v_mfma_f32_32x32x16_bf16 v[96:111], v[6:9], v[184:187], v[96:111]
	ds_read_b128 v[2:5], v0 offset:7168
	ds_read_b128 v[6:9], v0 offset:7680
	s_waitcnt lgkmcnt(1)
	v_mfma_f32_32x32x16_bf16 v[112:127], v[2:5], v[188:191], v[112:127]
	v_lshrrev_b64 v[2:3], s8, v[152:153]
	v_and_b32_e32 v0, 1, v2
	v_cmp_eq_u32_e64 s[2:3], 1, v0
	v_subrev_u32_e32 v0, s9, v155
	v_cvt_f32_i32_e32 v0, v0
	s_mov_b64 s[8:9], -1
	v_fma_f32 v0, -v240, v0, v249
	s_waitcnt lgkmcnt(0)
	v_mfma_f32_32x32x16_bf16 v[96:111], v[6:9], v[188:191], v[96:111]
	v_add_f32_e32 v3, v240, v0
	v_fma_f32 v2, 0, v240, v0
	s_cbranch_scc0 .LBB0_1327
	s_mov_b32 s8, 2.0
	v_cndmask_b32_e64 v4, -1, v154, s[2:3]
	s_mov_b32 s9, 0x40400000
	v_sub_u32_e32 v159, v4, v156
	v_pk_fma_f32 v[4:5], v[242:243], s[8:9], v[0:1] op_sel_hi:[1,1,0]
	s_mov_b32 s8, 0x41000000
	s_mov_b32 s9, 0x41100000
	v_pk_fma_f32 v[6:7], v[242:243], s[8:9], v[0:1] op_sel_hi:[1,1,0]
	s_mov_b32 s8, 0x41200000
	s_mov_b32 s9, 0x41300000
	v_pk_fma_f32 v[8:9], v[242:243], s[8:9], v[0:1] op_sel_hi:[1,1,0]
	s_mov_b32 s8, 0x41800000
	s_mov_b32 s9, 0x41880000
	v_pk_fma_f32 v[10:11], v[242:243], s[8:9], v[0:1] op_sel_hi:[1,1,0]
	s_mov_b32 s8, 0x41900000
	s_mov_b32 s9, 0x41980000
	v_pk_fma_f32 v[12:13], v[242:243], s[8:9], v[0:1] op_sel_hi:[1,1,0]
	s_mov_b32 s8, 0x41c00000
	s_mov_b32 s9, 0x41c80000
	v_pk_fma_f32 v[14:15], v[242:243], s[8:9], v[0:1] op_sel_hi:[1,1,0]
	s_mov_b32 s8, 0x41d00000
	s_mov_b32 s9, 0x41d80000
	v_pk_fma_f32 v[80:81], v[242:243], s[8:9], v[0:1] op_sel_hi:[1,1,0]
	v_cmp_lt_i32_e32 vcc, 26, v159
	v_pk_fma_f32 v[80:81], v[126:127], s[14:15], v[80:81] op_sel_hi:[1,0,1]
	v_pk_fma_f32 v[14:15], v[124:125], s[14:15], v[14:15] op_sel_hi:[1,0,1]
	v_cndmask_b32_e32 v95, v248, v81, vcc
	v_cmp_lt_i32_e32 vcc, 25, v159
	v_pk_fma_f32 v[12:13], v[122:123], s[14:15], v[12:13] op_sel_hi:[1,0,1]
	v_pk_fma_f32 v[10:11], v[120:121], s[14:15], v[10:11] op_sel_hi:[1,0,1]
	v_cndmask_b32_e32 v94, v248, v80, vcc
	v_cmp_lt_i32_e32 vcc, 24, v159
	v_pk_fma_f32 v[8:9], v[118:119], s[14:15], v[8:9] op_sel_hi:[1,0,1]
	v_pk_fma_f32 v[6:7], v[116:117], s[14:15], v[6:7] op_sel_hi:[1,0,1]
	v_cndmask_b32_e32 v93, v248, v15, vcc
	v_cmp_lt_i32_e32 vcc, 23, v159
	v_pk_fma_f32 v[4:5], v[114:115], s[14:15], v[4:5] op_sel_hi:[1,0,1]
	s_mov_b32 s8, 0x42680000
	v_cndmask_b32_e32 v92, v248, v14, vcc
	v_cmp_lt_i32_e32 vcc, 18, v159
	v_mov_b32_e32 v241, v240
	s_mov_b32 s9, 0x426c0000
	v_cndmask_b32_e32 v91, v248, v13, vcc
	v_cmp_lt_i32_e32 vcc, 17, v159
	v_pk_fma_f32 v[128:129], v[112:113], s[14:15], v[2:3] op_sel_hi:[1,0,1]
	s_nop 0
	v_cndmask_b32_e32 v90, v248, v12, vcc
	v_cmp_lt_i32_e32 vcc, 16, v159
	s_nop 1
	v_cndmask_b32_e32 v89, v248, v11, vcc
	v_cmp_lt_i32_e32 vcc, 15, v159
	s_nop 1
	v_cndmask_b32_e32 v88, v248, v10, vcc
	v_cmp_lt_i32_e32 vcc, 10, v159
	s_nop 1
	v_cndmask_b32_e32 v87, v248, v9, vcc
	v_cmp_lt_i32_e32 vcc, 9, v159
	s_nop 1
	v_cndmask_b32_e32 v86, v248, v8, vcc
	v_cmp_lt_i32_e32 vcc, 8, v159
	s_nop 1
	v_cndmask_b32_e32 v85, v248, v7, vcc
	v_cmp_lt_i32_e32 vcc, 7, v159
	s_nop 1
	v_cndmask_b32_e32 v84, v248, v6, vcc
	v_cmp_lt_i32_e32 vcc, 2, v159
	s_nop 1
	v_cndmask_b32_e32 v83, v248, v5, vcc
	v_cmp_lt_i32_e32 vcc, 1, v159
	s_nop 1
	v_cndmask_b32_e32 v82, v248, v4, vcc
	v_pk_fma_f32 v[4:5], v[240:241], s[8:9], v[0:1] op_sel_hi:[1,1,0]
	s_mov_b32 s8, 0x42600000
	s_mov_b32 s9, 0x42640000
	v_pk_fma_f32 v[6:7], v[240:241], s[8:9], v[0:1] op_sel_hi:[1,1,0]
	s_mov_b32 s8, 0x42480000
	s_mov_b32 s9, 0x424c0000
	v_pk_fma_f32 v[8:9], v[240:241], s[8:9], v[0:1] op_sel_hi:[1,1,0]
	s_mov_b32 s8, 0x42400000
	s_mov_b32 s9, 0x42440000
	v_pk_fma_f32 v[10:11], v[240:241], s[8:9], v[0:1] op_sel_hi:[1,1,0]
	s_mov_b32 s8, 0x42280000
	s_mov_b32 s9, 0x422c0000
	v_pk_fma_f32 v[12:13], v[240:241], s[8:9], v[0:1] op_sel_hi:[1,1,0]
	s_mov_b32 s8, 0x42200000
	s_mov_b32 s9, 0x42240000
	v_cmp_lt_i32_e32 vcc, 0, v159
	v_pk_fma_f32 v[14:15], v[240:241], s[8:9], v[0:1] op_sel_hi:[1,1,0]
	s_mov_b32 s8, 0x42080000
	v_cndmask_b32_e32 v81, v248, v129, vcc
	v_cmp_lt_i32_e32 vcc, -1, v159
	s_mov_b32 s9, 0x420c0000
	v_pk_fma_f32 v[4:5], v[110:111], s[14:15], v[4:5] op_sel_hi:[1,0,1]
	v_cndmask_b32_e32 v80, v248, v128, vcc
	v_pk_fma_f32 v[128:129], v[240:241], s[8:9], v[0:1] op_sel_hi:[1,1,0]
	s_mov_b32 s8, 0x42000000
	s_mov_b32 s9, 0x42040000
	v_pk_fma_f32 v[130:131], v[244:245], s[8:9], v[0:1] op_sel_hi:[1,1,0]
	v_pk_fma_f32 v[160:161], v[98:99], s[14:15], v[128:129] op_sel_hi:[1,0,1]
	v_pk_fma_f32 v[128:129], v[96:97], s[14:15], v[130:131] op_sel_hi:[1,0,1]
	v_cmp_lt_i32_e32 vcc, 32, v159
	v_pk_fma_f32 v[6:7], v[108:109], s[14:15], v[6:7] op_sel_hi:[1,0,1]
	v_pk_fma_f32 v[8:9], v[106:107], s[14:15], v[8:9] op_sel_hi:[1,0,1]
	v_cndmask_b32_e32 v129, v248, v129, vcc
	v_cmp_lt_i32_e32 vcc, 31, v159
	v_pk_fma_f32 v[10:11], v[104:105], s[14:15], v[10:11] op_sel_hi:[1,0,1]
	v_pk_fma_f32 v[12:13], v[102:103], s[14:15], v[12:13] op_sel_hi:[1,0,1]
	v_cndmask_b32_e32 v128, v248, v128, vcc
	v_cmp_lt_i32_e32 vcc, 58, v159
	v_pk_fma_f32 v[14:15], v[100:101], s[14:15], v[14:15] op_sel_hi:[1,0,1]
	s_mov_b64 s[8:9], 0
	v_cndmask_b32_e32 v143, v248, v5, vcc
	v_cmp_lt_i32_e32 vcc, 57, v159
	s_nop 1
	v_cndmask_b32_e32 v142, v248, v4, vcc
	v_cmp_lt_i32_e32 vcc, 56, v159
	s_nop 1
	v_cndmask_b32_e32 v141, v248, v7, vcc
	v_cmp_lt_i32_e32 vcc, 55, v159
	s_nop 1
	v_cndmask_b32_e32 v140, v248, v6, vcc
	v_cmp_lt_i32_e32 vcc, 50, v159
	s_nop 1
	v_cndmask_b32_e32 v139, v248, v9, vcc
	v_cmp_lt_i32_e32 vcc, 49, v159
	s_nop 1
	v_cndmask_b32_e32 v138, v248, v8, vcc
	v_cmp_lt_i32_e32 vcc, 48, v159
	s_nop 1
	v_cndmask_b32_e32 v137, v248, v11, vcc
	v_cmp_lt_i32_e32 vcc, 47, v159
	s_nop 1
	v_cndmask_b32_e32 v136, v248, v10, vcc
	v_cmp_lt_i32_e32 vcc, 42, v159
	s_nop 1
	v_cndmask_b32_e32 v135, v248, v13, vcc
	v_cmp_lt_i32_e32 vcc, 41, v159
	s_nop 1
	v_cndmask_b32_e32 v134, v248, v12, vcc
	v_cmp_lt_i32_e32 vcc, 40, v159
	s_nop 1
	v_cndmask_b32_e32 v133, v248, v15, vcc
	v_cmp_lt_i32_e32 vcc, 39, v159
	s_nop 1
	v_cndmask_b32_e32 v132, v248, v14, vcc
	v_cmp_lt_i32_e32 vcc, 34, v159
	s_nop 1
	v_cndmask_b32_e32 v131, v248, v161, vcc
	v_cmp_lt_i32_e32 vcc, 33, v159
	s_nop 1
	v_cndmask_b32_e32 v130, v248, v160, vcc

; #define LAS __attribute__((address_space(3)))
; #define NSA_LOADT(kb_, vb_, pitch_) do { int ln_ = lane; asm volatile("" : "+v"(ln_));   \
;         kreg = *(const u32x4*)((kb_) + (unsigned)(ln_ * (pitch_) + wid * 8)); vreg = *(const u32x4*)((vb_) + (unsigned)((16 * (wid & 3) + (ln_ >> 2)) * (pitch_) + (wid >> 2) * 32 + (ln_ & 3) * 8)); } while (0)
; __device__ __forceinline__ void nsa_qk(f32x16& p0, f32x16& p1, const LAS unsigned char* kslot, const bf16x8v (&qr)[4], int r32, int hi) {
;     const LAS unsigned char* kb = kslot + hi * 1024 + r32 * 16;
;     f32x16 z;
; #pragma unroll
;     for (int r = 0; r < 16; ++r) z[r] = 0.f;
;     p0 = z; p1 = z;
; #pragma unroll
;     for (int d0 = 0; d0 < 4; ++d0) { const bf16x8v b0 = *(const LAS bf16x8v*)(kb + d0 * 2048), b1 = *(const LAS bf16x8v*)(kb + d0 * 2048 + 512);
;         p0 = __builtin_amdgcn_mfma_f32_32x32x16_bf16(b0, qr[d0], p0, 0, 0, 0); p1 = __builtin_amdgcn_mfma_f32_32x32x16_bf16(b1, qr[d0], p1, 0, 0, 0); }
; }
; __device__ __forceinline__ void nsa_unit(const Ctx& c, int l, int b, int n, int qt) {
;     ...
;             const bool more = kt > klast;
;             if (more) NSA_LOADT(Kb + (size_t)(kt - 1) * 64 * HW, Vb + (size_t)(kt - 1) * 64 * HW, HW);
;             f32x16 p0, p1;
;             nsa_qk(p0, p1, lds + NL_KS + cur * 8192, qr, r32, hi);
.LBB0_1340:
	s_lshl_b32 s30, s25, 13
	v_add_u32_e32 v0, s30, v236
	ds_read_b128 v[2:5], v0 offset:1024
	ds_read_b128 v[6:9], v0 offset:1536
	s_add_i32 s19, s13, 1
	s_cmp_gt_i32 s19, s20
	s_cselect_b64 s[16:17], -1, 0
	s_cmp_le_i32 s19, s20
	s_cbranch_scc1 .LBB0_1342
	v_mov_b32_e32 v228, v247
	s_mul_i32 s8, s13, 0x70000
	s_mul_hi_u32 s9, s13, 0x70000
	s_add_u32 s8, s28, s8
	v_mul_lo_u32 v224, v228, s21
	s_addc_u32 s9, s29, s9
	s_add_u32 s8, s8, 0x800
	s_addc_u32 s9, s9, 0
	v_mov_b32_e32 v225, 0
	v_add_u32_e32 v224, s1, v224
	v_lshl_add_u64 v[226:227], v[224:225], 1, s[8:9]
	v_lshrrev_b32_e32 v224, 2, v228
	v_add_u32_e32 v224, s22, v224
	v_mul_lo_u32 v224, v224, s21
	s_add_u32 s8, s8, 0x100
	s_addc_u32 s9, s9, 0
	v_add_u32_e32 v224, s23, v224
	v_lshlrev_b32_e32 v228, 3, v228
	v_and_or_b32 v224, v228, 24, v224
	v_lshl_add_u64 v[228:229], v[224:225], 1, s[8:9]
	s_xor_b32 s8, s25, 1
	s_lshl_b32 s8, s8, 13
	s_add_i32 s8, s8, s26
	s_add_i32 m0, s8, 0x400
	s_nop 0
	global_load_lds_dwordx4 v[226:227], off
	s_add_i32 m0, s8, 0x4400
	s_nop 0
	global_load_lds_dwordx4 v[228:229], off
; __device__ __forceinline__ void nsa_scores(f32x16& p0, f32x16& p1, float Ap, float slk, int thrp, bool flip) {
; #pragma unroll
;     for (int r = 0; r < 16; ++r) { const int cr = (r & 3) + 8 * (r >> 2);
;         const bool v0 = (cr <= thrp) != flip, v1 = (cr + 32 <= thrp) != flip;
;         p0[r] = v0 ? fmaf(p0[r], C2S, fmaf(slk, (float)cr, Ap)) : SNEG; p1[r] = v1 ? fmaf(p1[r], C2S, fmaf(slk, (float)(cr + 32), Ap)) : SNEG; }
; }
; __device__ __forceinline__ void nsa_unit(const Ctx& c, int l, int b, int n, int qt) {
;     ...
;             nsa_qk(p0, p1, lds + NL_KS + cur * 8192, qr, r32, hi);
;             const int dl = qt - kt;
;             if (dl != 0 && dl != 8) nsa_scores_all(p0, p1, -sl2 * (float)(64 * dl + tq) + sl2 * (float)(4 * hi), sl2);
;             else nsa_scores(p0, p1, -sl2 * (float)(64 * dl + tq) + sl2 * (float)(4 * hi), sl2, tq - 4 * hi, dl == 8);
.LBB0_1342:
	s_cmp_lg_u32 s24, 0
	s_cselect_b64 s[8:9], -1, 0
	s_cmpk_lg_i32 s24, 0x200
	s_waitcnt lgkmcnt(1)
	v_mfma_f32_32x32x16_bf16 v[160:175], v[2:5], v[176:179], 0
	s_cselect_b64 vcc, -1, 0
	s_and_b64 vcc, s[8:9], vcc
	s_mov_b64 s[8:9], -1
	s_andn2_b64 vcc, exec, vcc
	s_waitcnt lgkmcnt(0)
	v_mfma_f32_32x32x16_bf16 v[144:159], v[6:9], v[176:179], 0
	ds_read_b128 v[2:5], v0 offset:3072
	ds_read_b128 v[6:9], v0 offset:3584
	s_waitcnt lgkmcnt(1)
	v_mfma_f32_32x32x16_bf16 v[160:175], v[2:5], v[180:183], v[160:175]
	s_waitcnt lgkmcnt(0)
	v_mfma_f32_32x32x16_bf16 v[144:159], v[6:9], v[180:183], v[144:159]
	ds_read_b128 v[2:5], v0 offset:5120
	ds_read_b128 v[6:9], v0 offset:5632
	s_waitcnt lgkmcnt(1)
	v_mfma_f32_32x32x16_bf16 v[160:175], v[2:5], v[184:187], v[160:175]
	s_waitcnt lgkmcnt(0)
	v_mfma_f32_32x32x16_bf16 v[144:159], v[6:9], v[184:187], v[144:159]
	ds_read_b128 v[2:5], v0 offset:7168
	ds_read_b128 v[6:9], v0 offset:7680
	v_add_u32_e32 v0, s33, v235
	v_add_u32_e32 v0, s24, v0
	v_cvt_f32_u32_e32 v0, v0
	v_fma_f32 v0, -v240, v0, v249
	s_waitcnt lgkmcnt(1)
	v_mfma_f32_32x32x16_bf16 v[160:175], v[2:5], v[188:191], v[160:175]
	v_add_f32_e32 v3, v240, v0
	v_fma_f32 v2, 0, v240, v0
	s_waitcnt lgkmcnt(0)
	v_mfma_f32_32x32x16_bf16 v[144:159], v[6:9], v[188:191], v[144:159]
	s_cbranch_vccz .LBB0_1344
	s_cmpk_eq_i32 s24, 0x200
	s_cselect_b64 s[8:9], -1, 0
	s_nop 4
	v_fmamk_f32 v4, v160, 0x3e38aa3b, v2
	s_xor_b64 vcc, s[42:43], s[8:9]
	v_cndmask_b32_e32 v128, v4, v248, vcc
	v_fmamk_f32 v4, v240, 0x42000000, v0
	v_fmac_f32_e32 v4, 0x3e38aa3b, v144
	s_xor_b64 vcc, s[44:45], s[8:9]
	v_cndmask_b32_e32 v112, v4, v248, vcc
	v_fmamk_f32 v4, v161, 0x3e38aa3b, v3
	s_xor_b64 vcc, s[46:47], s[8:9]
	v_cndmask_b32_e32 v129, v4, v248, vcc
	v_fmamk_f32 v4, v240, 0x42040000, v0
	v_fmac_f32_e32 v4, 0x3e38aa3b, v145
	s_xor_b64 vcc, s[48:49], s[8:9]
	v_cndmask_b32_e32 v113, v4, v248, vcc
	v_fma_f32 v4, 2.0, v240, v0
	v_fmac_f32_e32 v4, 0x3e38aa3b, v162
	s_xor_b64 vcc, s[50:51], s[8:9]
	v_cndmask_b32_e32 v130, v4, v248, vcc
	v_fmamk_f32 v4, v240, 0x42080000, v0
	v_fmac_f32_e32 v4, 0x3e38aa3b, v146
	s_xor_b64 vcc, s[52:53], s[8:9]
	v_cndmask_b32_e32 v114, v4, v248, vcc
	v_fmamk_f32 v4, v240, 0x40400000, v0
	v_fmac_f32_e32 v4, 0x3e38aa3b, v163
	s_xor_b64 vcc, s[54:55], s[8:9]
	v_cndmask_b32_e32 v131, v4, v248, vcc
	v_fmamk_f32 v4, v240, 0x420c0000, v0
	v_fmac_f32_e32 v4, 0x3e38aa3b, v147
	s_xor_b64 vcc, s[56:57], s[8:9]
	v_cndmask_b32_e32 v115, v4, v248, vcc
	v_fmamk_f32 v4, v240, 0x41000000, v0
	v_fmac_f32_e32 v4, 0x3e38aa3b, v164
	s_xor_b64 vcc, s[58:59], s[8:9]
	v_cndmask_b32_e32 v132, v4, v248, vcc
	v_fmamk_f32 v4, v240, 0x42200000, v0
	v_fmac_f32_e32 v4, 0x3e38aa3b, v148
	s_xor_b64 vcc, s[60:61], s[8:9]
	v_cndmask_b32_e32 v116, v4, v248, vcc
	v_fmamk_f32 v4, v240, 0x41100000, v0
	v_fmac_f32_e32 v4, 0x3e38aa3b, v165
	s_xor_b64 vcc, s[62:63], s[8:9]
	v_cndmask_b32_e32 v133, v4, v248, vcc
	v_fmamk_f32 v4, v240, 0x42240000, v0
	v_fmac_f32_e32 v4, 0x3e38aa3b, v149
	s_xor_b64 vcc, s[64:65], s[8:9]
	v_cndmask_b32_e32 v117, v4, v248, vcc
	v_fmamk_f32 v4, v240, 0x41200000, v0
	v_fmac_f32_e32 v4, 0x3e38aa3b, v166
	s_xor_b64 vcc, s[66:67], s[8:9]
	v_cndmask_b32_e32 v134, v4, v248, vcc
	v_fmamk_f32 v4, v240, 0x42280000, v0
	v_fmac_f32_e32 v4, 0x3e38aa3b, v150
	s_xor_b64 vcc, s[68:69], s[8:9]
	v_cndmask_b32_e32 v118, v4, v248, vcc
	v_fmamk_f32 v4, v240, 0x41300000, v0
	v_fmac_f32_e32 v4, 0x3e38aa3b, v167
	s_xor_b64 vcc, s[70:71], s[8:9]
	v_cndmask_b32_e32 v135, v4, v248, vcc
	v_fmamk_f32 v4, v240, 0x422c0000, v0
	v_fmac_f32_e32 v4, 0x3e38aa3b, v151
	s_xor_b64 vcc, s[72:73], s[8:9]
	v_cndmask_b32_e32 v119, v4, v248, vcc
	v_fmamk_f32 v4, v240, 0x41800000, v0
	v_fmac_f32_e32 v4, 0x3e38aa3b, v168
	s_xor_b64 vcc, s[74:75], s[8:9]
	v_cndmask_b32_e32 v136, v4, v248, vcc
	v_fmamk_f32 v4, v240, 0x42400000, v0
	v_fmac_f32_e32 v4, 0x3e38aa3b, v152
	s_xor_b64 vcc, s[76:77], s[8:9]
	v_cndmask_b32_e32 v120, v4, v248, vcc
	v_fmamk_f32 v4, v240, 0x41880000, v0
	v_fmac_f32_e32 v4, 0x3e38aa3b, v169
	s_xor_b64 vcc, s[78:79], s[8:9]
	v_cndmask_b32_e32 v137, v4, v248, vcc
	v_fmamk_f32 v4, v240, 0x42440000, v0
	v_fmac_f32_e32 v4, 0x3e38aa3b, v153
	s_xor_b64 vcc, s[80:81], s[8:9]
	v_cndmask_b32_e32 v121, v4, v248, vcc
	v_fmamk_f32 v4, v240, 0x41900000, v0
	v_fmac_f32_e32 v4, 0x3e38aa3b, v170
	s_xor_b64 vcc, s[82:83], s[8:9]
	v_cndmask_b32_e32 v138, v4, v248, vcc
	v_fmamk_f32 v4, v240, 0x42480000, v0
	v_fmac_f32_e32 v4, 0x3e38aa3b, v154
	s_xor_b64 vcc, s[84:85], s[8:9]
	v_cndmask_b32_e32 v122, v4, v248, vcc
	v_fmamk_f32 v4, v240, 0x41980000, v0
	v_fmac_f32_e32 v4, 0x3e38aa3b, v171
	s_xor_b64 vcc, s[86:87], s[8:9]
	v_cndmask_b32_e32 v139, v4, v248, vcc
	v_fmamk_f32 v4, v240, 0x424c0000, v0
	v_fmac_f32_e32 v4, 0x3e38aa3b, v155
	s_xor_b64 vcc, s[88:89], s[8:9]
	v_cndmask_b32_e32 v123, v4, v248, vcc
	v_fmamk_f32 v4, v240, 0x41c00000, v0
	v_fmac_f32_e32 v4, 0x3e38aa3b, v172
	s_xor_b64 vcc, s[90:91], s[8:9]
	v_cndmask_b32_e32 v140, v4, v248, vcc
	v_fmamk_f32 v4, v240, 0x42600000, v0
	v_fmac_f32_e32 v4, 0x3e38aa3b, v156
	s_xor_b64 vcc, s[92:93], s[8:9]
	v_cndmask_b32_e32 v124, v4, v248, vcc
	v_fmamk_f32 v4, v240, 0x41c80000, v0
	v_fmac_f32_e32 v4, 0x3e38aa3b, v173
	s_xor_b64 vcc, s[94:95], s[8:9]
	v_cndmask_b32_e32 v141, v4, v248, vcc
	v_fmamk_f32 v4, v240, 0x42640000, v0
	v_fmac_f32_e32 v4, 0x3e38aa3b, v157
	s_xor_b64 vcc, s[96:97], s[8:9]
	v_cndmask_b32_e32 v125, v4, v248, vcc
	v_fmamk_f32 v4, v240, 0x41d00000, v0
	v_fmac_f32_e32 v4, 0x3e38aa3b, v174
	s_xor_b64 vcc, s[36:37], s[8:9]
	v_cndmask_b32_e32 v142, v4, v248, vcc
	v_fmamk_f32 v4, v240, 0x42680000, v0
	v_fmac_f32_e32 v4, 0x3e38aa3b, v158
	s_xor_b64 vcc, s[2:3], s[8:9]
	v_cndmask_b32_e32 v126, v4, v248, vcc
	v_fmamk_f32 v4, v240, 0x41d80000, v0
	v_fmac_f32_e32 v4, 0x3e38aa3b, v175
	s_xor_b64 vcc, s[4:5], s[8:9]
	v_cndmask_b32_e32 v143, v4, v248, vcc
	v_fmamk_f32 v4, v240, 0x426c0000, v0
	v_fmac_f32_e32 v4, 0x3e38aa3b, v159
	s_xor_b64 vcc, s[6:7], s[8:9]
	v_cndmask_b32_e32 v127, v4, v248, vcc
	s_mov_b64 s[8:9], 0
